# v33 plus: layer-1 MLP2 panel sync also drops the L1 invalidate (its reader side uses only sc1 loads and constants)
# baseline (speedup 1.0000x reference)
; template <int EPI>
; DI void gemm_epilogue(const Params& p, int layer, f32x4 (&acc)[2][2][4][2], int brow, int bcol, int pn, int wr, int wc,
;                       int fr, int fq, char* smem, int ksplit = -1) {
;     ...
;       __builtin_amdgcn_fence(__ATOMIC_ACQUIRE, "agent");
;     }
;     __syncthreads();
;     float rsv[2][4];
; #pragma unroll
;     for (int ai = 0; ai < 2; ++ai)
; #pragma unroll
;       for (int m = 0; m < 4; ++m)
;         rsv[ai][m] = __hip_atomic_load(p.rowssF + brow + ai * 128 + wr * 64 + m * 16 + fr, __ATOMIC_RELAXED, __HIP_MEMORY_SCOPE_AGENT);
;     f32x4 fg[2][2];
; #pragma unroll
;     for (int bj = 0; bj < 2; ++bj)
; #pragma unroll
;       for (int n = 0; n < 2; ++n) fg[bj][n] = *(const f32x4*)(p.final_g + colb + bj * 128 + n * 4);
; #pragma unroll
;     for (int ai = 0; ai < 2; ++ai)
; #pragma unroll
;       for (int m = 0; m < 4; ++m) {
;         __builtin_amdgcn_sched_barrier(0);
;         const float rs = __builtin_amdgcn_rsqf(rsv[ai][m] * (1.f / DM) + EPSN);
;         float* drow = p.out + (size_t)(brow + ai * 128 + wr * 64 + m * 16 + fr) * DM;
; #pragma unroll
;         for (int bj = 0; bj < 2; ++bj)
; #pragma unroll
;           for (int n = 0; n < 2; ++n) *(f32x4*)(drow + colb + bj * 128 + n * 4) = acc[ai][bj][m][n] * rs * fg[bj][n];
.LBB0_1175:
.LBB0_1176:
	s_or_b64 exec, exec, s[16:17]
	s_lshl_b64 s[14:15], s[18:19], 2
	s_add_u32 s14, s7, s14
	s_addc_u32 s15, s43, s15
	s_barrier
	global_load_dword v131, v187, s[14:15] sc1
	global_load_dword v133, v187, s[14:15] offset:64 sc1
	global_load_dword v136, v187, s[14:15] offset:128 sc1
	global_load_dword v137, v187, s[14:15] offset:192 sc1
	global_load_dword v138, v187, s[14:15] offset:512 sc1
	global_load_dword v139, v187, s[14:15] offset:576 sc1
	global_load_dword v140, v187, s[14:15] offset:640 sc1
	global_load_dword v141, v187, s[14:15] offset:704 sc1
	v_readlane_b32 s60, v252, 0
	v_readlane_b32 s66, v252, 6
	v_readlane_b32 s67, v252, 7
	s_mov_b64 s[46:47], s[66:67]
	v_lshl_add_u64 v[6:7], s[46:47], 0, v[178:179]
	global_load_dwordx4 v[10:13], v[6:7], off offset:16
	global_load_dwordx4 v[14:17], v[6:7], off
	global_load_dwordx4 v[2:5], v[6:7], off offset:528
	s_nop 0
	global_load_dwordx4 v[6:9], v[6:7], off offset:512
	v_readlane_b32 s68, v252, 8
	v_readlane_b32 s69, v252, 9
	v_readlane_b32 s70, v252, 10
	v_readlane_b32 s71, v252, 11
	v_readlane_b32 s72, v252, 12
	v_readlane_b32 s73, v252, 13
	v_readlane_b32 s74, v252, 14
	v_readlane_b32 s75, v252, 15
	s_mov_b64 s[48:49], s[68:69]
	s_add_i32 s14, s18, s6
	v_readlane_b32 s61, v252, 1
	v_readlane_b32 s62, v252, 2
	v_readlane_b32 s63, v252, 3
	v_readlane_b32 s64, v252, 4
	v_readlane_b32 s65, v252, 5
	s_mov_b64 s[50:51], s[70:71]
	s_mov_b64 s[52:53], s[72:73]
	s_mov_b64 s[54:55], s[74:75]
	v_or_b32_e32 v130, s14, v186
	s_waitcnt vmcnt(11)
	v_fmamk_f32 v131, v131, 0x3a800000, v236
	v_rsq_f32_e32 v132, v131
	v_ashrrev_i32_e32 v131, 31, v130
	v_lshlrev_b64 v[134:135], 12, v[130:131]
	v_lshl_add_u64 v[134:135], s[48:49], 0, v[134:135]
	s_waitcnt vmcnt(10)
	v_pk_mul_f32 v[126:127], v[126:127], v[132:133] op_sel_hi:[1,0]
	v_pk_mul_f32 v[128:129], v[128:129], v[132:133] op_sel_hi:[1,0]
	v_pk_mul_f32 v[122:123], v[122:123], v[132:133] op_sel_hi:[1,0]
	v_pk_mul_f32 v[124:125], v[124:125], v[132:133] op_sel_hi:[1,0]
	v_pk_mul_f32 v[118:119], v[118:119], v[132:133] op_sel_hi:[1,0]
	v_pk_mul_f32 v[120:121], v[120:121], v[132:133] op_sel_hi:[1,0]
	v_pk_mul_f32 v[114:115], v[114:115], v[132:133] op_sel_hi:[1,0]
	v_pk_mul_f32 v[116:117], v[116:117], v[132:133] op_sel_hi:[1,0]
	v_lshl_add_u64 v[134:135], v[134:135], 0, v[178:179]
	s_waitcnt vmcnt(2)
	v_pk_mul_f32 v[128:129], v[128:129], v[16:17]
	v_pk_mul_f32 v[126:127], v[126:127], v[14:15]
	v_pk_mul_f32 v[124:125], v[124:125], v[12:13]
	v_pk_mul_f32 v[122:123], v[122:123], v[10:11]
	s_waitcnt vmcnt(0)
	v_pk_mul_f32 v[120:121], v[120:121], v[8:9]
	v_pk_mul_f32 v[118:119], v[118:119], v[6:7]
	v_pk_mul_f32 v[116:117], v[116:117], v[4:5]
	v_pk_mul_f32 v[114:115], v[114:115], v[2:3]
	global_store_dwordx4 v[134:135], v[126:129], off
	global_store_dwordx4 v[134:135], v[122:125], off offset:16
	global_store_dwordx4 v[134:135], v[118:121], off offset:512
	global_store_dwordx4 v[134:135], v[114:117], off offset:528
	s_nop 1
	v_fmamk_f32 v114, v133, 0x3a800000, v236
	v_rsq_f32_e32 v118, v114
	v_or_b32_e32 v114, 16, v130
	v_ashrrev_i32_e32 v115, 31, v114
	v_lshlrev_b64 v[114:115], 12, v[114:115]
	v_lshl_add_u64 v[114:115], s[48:49], 0, v[114:115]
	v_lshl_add_u64 v[120:121], v[114:115], 0, v[178:179]
	v_pk_mul_f32 v[114:115], v[158:159], v[118:119] op_sel_hi:[1,0]
	v_pk_mul_f32 v[116:117], v[160:161], v[118:119] op_sel_hi:[1,0]
	v_pk_mul_f32 v[114:115], v[14:15], v[114:115]
	v_pk_mul_f32 v[116:117], v[16:17], v[116:117]
	global_store_dwordx4 v[120:121], v[114:117], off
	s_nop 1
	v_pk_mul_f32 v[114:115], v[154:155], v[118:119] op_sel_hi:[1,0]
	v_pk_mul_f32 v[116:117], v[156:157], v[118:119] op_sel_hi:[1,0]
	v_pk_mul_f32 v[114:115], v[114:115], v[10:11]
	v_pk_mul_f32 v[116:117], v[116:117], v[12:13]
	global_store_dwordx4 v[120:121], v[114:117], off offset:16
	s_nop 1
	v_pk_mul_f32 v[114:115], v[150:151], v[118:119] op_sel_hi:[1,0]
	v_pk_mul_f32 v[116:117], v[152:153], v[118:119] op_sel_hi:[1,0]
	v_pk_mul_f32 v[114:115], v[114:115], v[6:7]
	v_pk_mul_f32 v[116:117], v[116:117], v[8:9]
	global_store_dwordx4 v[120:121], v[114:117], off offset:512
	s_nop 1
	v_pk_mul_f32 v[114:115], v[146:147], v[118:119] op_sel_hi:[1,0]
	v_pk_mul_f32 v[116:117], v[148:149], v[118:119] op_sel_hi:[1,0]
	v_pk_mul_f32 v[114:115], v[114:115], v[2:3]
	v_pk_mul_f32 v[116:117], v[116:117], v[4:5]
	global_store_dwordx4 v[120:121], v[114:117], off offset:528
	s_nop 1
	v_fmamk_f32 v114, v136, 0x3a800000, v236
	v_rsq_f32_e32 v114, v114
	v_or_b32_e32 v116, 32, v130
	v_ashrrev_i32_e32 v117, 31, v116
	v_lshlrev_b64 v[116:117], 12, v[116:117]
	v_lshl_add_u64 v[116:117], s[48:49], 0, v[116:117]
	v_pk_mul_f32 v[94:95], v[94:95], v[114:115] op_sel_hi:[1,0]
	v_pk_mul_f32 v[96:97], v[96:97], v[114:115] op_sel_hi:[1,0]
	v_pk_mul_f32 v[90:91], v[90:91], v[114:115] op_sel_hi:[1,0]
	v_pk_mul_f32 v[92:93], v[92:93], v[114:115] op_sel_hi:[1,0]
	v_pk_mul_f32 v[86:87], v[86:87], v[114:115] op_sel_hi:[1,0]
	v_pk_mul_f32 v[88:89], v[88:89], v[114:115] op_sel_hi:[1,0]
	v_pk_mul_f32 v[82:83], v[82:83], v[114:115] op_sel_hi:[1,0]
	v_pk_mul_f32 v[84:85], v[84:85], v[114:115] op_sel_hi:[1,0]
	v_lshl_add_u64 v[116:117], v[116:117], 0, v[178:179]
	v_pk_mul_f32 v[96:97], v[16:17], v[96:97]
	v_pk_mul_f32 v[94:95], v[14:15], v[94:95]
	v_pk_mul_f32 v[92:93], v[12:13], v[92:93]
	v_pk_mul_f32 v[90:91], v[10:11], v[90:91]
	v_pk_mul_f32 v[88:89], v[88:89], v[8:9]
	v_pk_mul_f32 v[86:87], v[86:87], v[6:7]
	v_pk_mul_f32 v[84:85], v[84:85], v[4:5]
	v_pk_mul_f32 v[82:83], v[82:83], v[2:3]
	global_store_dwordx4 v[116:117], v[94:97], off
	global_store_dwordx4 v[116:117], v[90:93], off offset:16
; #define BAR __builtin_amdgcn_s_barrier()
; template <int EPI>
; DI void gemm_epilogue(const Params& p, int layer, f32x4 (&acc)[2][2][4][2], int brow, int bcol, int pn, int wr, int wc,
;                       int fr, int fq, char* smem, int ksplit = -1) {
;     ...
; #pragma unroll
;     for (int ai = 0; ai < 2; ++ai)
; #pragma unroll
;       for (int m = 0; m < 4; ++m) {
;         __builtin_amdgcn_sched_barrier(0);
;         const float rs = __builtin_amdgcn_rsqf(rsv[ai][m] * (1.f / DM) + EPSN);
;         float* drow = p.out + (size_t)(brow + ai * 128 + wr * 64 + m * 16 + fr) * DM;
; #pragma unroll
;         for (int bj = 0; bj < 2; ++bj)
; #pragma unroll
;           for (int n = 0; n < 2; ++n) *(f32x4*)(drow + colb + bj * 128 + n * 4) = acc[ai][bj][m][n] * rs * fg[bj][n];
;     ...
;     pm = npm; pn = npn; kq = nkq; cA = nA; cB = nB; ++ui;
;     if (wr == 1) BAR;
;   }
	global_store_dwordx4 v[116:117], v[86:89], off offset:512
	global_store_dwordx4 v[116:117], v[82:85], off offset:528
	s_nop 1
	v_fmamk_f32 v82, v137, 0x3a800000, v236
	v_rsq_f32_e32 v86, v82
	v_or_b32_e32 v82, 48, v130
	v_ashrrev_i32_e32 v83, 31, v82
	v_lshlrev_b64 v[82:83], 12, v[82:83]
	v_lshl_add_u64 v[82:83], s[48:49], 0, v[82:83]
	v_lshl_add_u64 v[88:89], v[82:83], 0, v[178:179]
	v_pk_mul_f32 v[82:83], v[110:111], v[86:87] op_sel_hi:[1,0]
	v_pk_mul_f32 v[84:85], v[112:113], v[86:87] op_sel_hi:[1,0]
	v_pk_mul_f32 v[82:83], v[14:15], v[82:83]
	v_pk_mul_f32 v[84:85], v[16:17], v[84:85]
	global_store_dwordx4 v[88:89], v[82:85], off
	s_nop 1
	v_pk_mul_f32 v[82:83], v[106:107], v[86:87] op_sel_hi:[1,0]
	v_pk_mul_f32 v[84:85], v[108:109], v[86:87] op_sel_hi:[1,0]
	v_pk_mul_f32 v[82:83], v[10:11], v[82:83]
	v_pk_mul_f32 v[84:85], v[12:13], v[84:85]
	global_store_dwordx4 v[88:89], v[82:85], off offset:16
	s_nop 1
	v_pk_mul_f32 v[82:83], v[102:103], v[86:87] op_sel_hi:[1,0]
	v_pk_mul_f32 v[84:85], v[104:105], v[86:87] op_sel_hi:[1,0]
	v_pk_mul_f32 v[82:83], v[6:7], v[82:83]
	v_pk_mul_f32 v[84:85], v[8:9], v[84:85]
	global_store_dwordx4 v[88:89], v[82:85], off offset:512
	s_nop 1
	v_pk_mul_f32 v[82:83], v[98:99], v[86:87] op_sel_hi:[1,0]
	v_pk_mul_f32 v[84:85], v[100:101], v[86:87] op_sel_hi:[1,0]
	v_pk_mul_f32 v[82:83], v[82:83], v[2:3]
	v_pk_mul_f32 v[84:85], v[84:85], v[4:5]
	global_store_dwordx4 v[88:89], v[82:85], off offset:528
	s_nop 1
	v_add_u32_e32 v82, 0x80, v130
	v_fmamk_f32 v83, v138, 0x3a800000, v236
	v_rsq_f32_e32 v84, v83
	v_ashrrev_i32_e32 v83, 31, v82
	v_lshlrev_b64 v[82:83], 12, v[82:83]
	v_lshl_add_u64 v[82:83], s[48:49], 0, v[82:83]
	v_pk_mul_f32 v[62:63], v[62:63], v[84:85] op_sel_hi:[1,0]
	v_pk_mul_f32 v[64:65], v[64:65], v[84:85] op_sel_hi:[1,0]
	v_pk_mul_f32 v[58:59], v[58:59], v[84:85] op_sel_hi:[1,0]
	v_pk_mul_f32 v[60:61], v[60:61], v[84:85] op_sel_hi:[1,0]
	v_pk_mul_f32 v[54:55], v[54:55], v[84:85] op_sel_hi:[1,0]
	v_pk_mul_f32 v[56:57], v[56:57], v[84:85] op_sel_hi:[1,0]
	v_pk_mul_f32 v[50:51], v[50:51], v[84:85] op_sel_hi:[1,0]
	v_pk_mul_f32 v[52:53], v[52:53], v[84:85] op_sel_hi:[1,0]
	v_lshl_add_u64 v[82:83], v[82:83], 0, v[178:179]
	v_pk_mul_f32 v[64:65], v[16:17], v[64:65]
	v_pk_mul_f32 v[62:63], v[14:15], v[62:63]
	v_pk_mul_f32 v[60:61], v[12:13], v[60:61]
	v_pk_mul_f32 v[58:59], v[10:11], v[58:59]
	v_pk_mul_f32 v[56:57], v[8:9], v[56:57]
	v_pk_mul_f32 v[54:55], v[6:7], v[54:55]
	v_pk_mul_f32 v[52:53], v[4:5], v[52:53]
	v_pk_mul_f32 v[50:51], v[2:3], v[50:51]
	global_store_dwordx4 v[82:83], v[62:65], off
	global_store_dwordx4 v[82:83], v[58:61], off offset:16
	global_store_dwordx4 v[82:83], v[54:57], off offset:512
	global_store_dwordx4 v[82:83], v[50:53], off offset:528
	s_nop 1
	v_fmamk_f32 v50, v139, 0x3a800000, v236
	v_rsq_f32_e32 v54, v50
	v_add_u32_e32 v50, 0x90, v130
	v_ashrrev_i32_e32 v51, 31, v50
	v_lshlrev_b64 v[50:51], 12, v[50:51]
	v_lshl_add_u64 v[50:51], s[48:49], 0, v[50:51]
	v_lshl_add_u64 v[56:57], v[50:51], 0, v[178:179]
	v_pk_mul_f32 v[50:51], v[78:79], v[54:55] op_sel_hi:[1,0]
	v_pk_mul_f32 v[52:53], v[80:81], v[54:55] op_sel_hi:[1,0]
	v_pk_mul_f32 v[50:51], v[14:15], v[50:51]
	v_pk_mul_f32 v[52:53], v[16:17], v[52:53]
	global_store_dwordx4 v[56:57], v[50:53], off
	s_nop 1
	v_pk_mul_f32 v[50:51], v[74:75], v[54:55] op_sel_hi:[1,0]
	v_pk_mul_f32 v[52:53], v[76:77], v[54:55] op_sel_hi:[1,0]
	v_pk_mul_f32 v[50:51], v[10:11], v[50:51]
	v_pk_mul_f32 v[52:53], v[12:13], v[52:53]
	global_store_dwordx4 v[56:57], v[50:53], off offset:16
	s_nop 1
	v_pk_mul_f32 v[50:51], v[70:71], v[54:55] op_sel_hi:[1,0]
	v_pk_mul_f32 v[52:53], v[72:73], v[54:55] op_sel_hi:[1,0]
	v_pk_mul_f32 v[50:51], v[6:7], v[50:51]
	v_pk_mul_f32 v[52:53], v[8:9], v[52:53]
	global_store_dwordx4 v[56:57], v[50:53], off offset:512
	s_nop 1
	v_pk_mul_f32 v[50:51], v[66:67], v[54:55] op_sel_hi:[1,0]
	v_pk_mul_f32 v[52:53], v[68:69], v[54:55] op_sel_hi:[1,0]
	v_pk_mul_f32 v[50:51], v[2:3], v[50:51]
	v_pk_mul_f32 v[52:53], v[4:5], v[52:53]
	global_store_dwordx4 v[56:57], v[50:53], off offset:528
	s_nop 1
	v_fmamk_f32 v50, v140, 0x3a800000, v236
	v_rsq_f32_e32 v50, v50
	v_add_u32_e32 v52, 0xa0, v130
	v_ashrrev_i32_e32 v53, 31, v52
	v_lshlrev_b64 v[52:53], 12, v[52:53]
	v_lshl_add_u64 v[52:53], s[48:49], 0, v[52:53]
	v_pk_mul_f32 v[30:31], v[30:31], v[50:51] op_sel_hi:[1,0]
	v_pk_mul_f32 v[32:33], v[32:33], v[50:51] op_sel_hi:[1,0]
	v_pk_mul_f32 v[26:27], v[26:27], v[50:51] op_sel_hi:[1,0]
	v_pk_mul_f32 v[28:29], v[28:29], v[50:51] op_sel_hi:[1,0]
	v_pk_mul_f32 v[22:23], v[22:23], v[50:51] op_sel_hi:[1,0]
	v_pk_mul_f32 v[24:25], v[24:25], v[50:51] op_sel_hi:[1,0]
	v_pk_mul_f32 v[18:19], v[18:19], v[50:51] op_sel_hi:[1,0]
	v_pk_mul_f32 v[20:21], v[20:21], v[50:51] op_sel_hi:[1,0]
	v_lshl_add_u64 v[52:53], v[52:53], 0, v[178:179]
	v_pk_mul_f32 v[32:33], v[16:17], v[32:33]
	v_pk_mul_f32 v[30:31], v[14:15], v[30:31]
	v_pk_mul_f32 v[28:29], v[12:13], v[28:29]
	v_pk_mul_f32 v[26:27], v[10:11], v[26:27]
	v_pk_mul_f32 v[24:25], v[8:9], v[24:25]
	v_pk_mul_f32 v[22:23], v[6:7], v[22:23]
	v_pk_mul_f32 v[20:21], v[4:5], v[20:21]
	v_pk_mul_f32 v[18:19], v[2:3], v[18:19]
	global_store_dwordx4 v[52:53], v[30:33], off
	global_store_dwordx4 v[52:53], v[26:29], off offset:16
	global_store_dwordx4 v[52:53], v[22:25], off offset:512
	global_store_dwordx4 v[52:53], v[18:21], off offset:528
	s_nop 1
	v_fmamk_f32 v18, v141, 0x3a800000, v236
	v_rsq_f32_e32 v18, v18
	v_add_u32_e32 v20, 0xb0, v130
	v_ashrrev_i32_e32 v21, 31, v20
	v_lshlrev_b64 v[20:21], 12, v[20:21]
	v_lshl_add_u64 v[20:21], s[48:49], 0, v[20:21]
	v_pk_mul_f32 v[22:23], v[46:47], v[18:19] op_sel_hi:[1,0]
	v_pk_mul_f32 v[24:25], v[48:49], v[18:19] op_sel_hi:[1,0]
	v_lshl_add_u64 v[20:21], v[20:21], 0, v[178:179]
	v_pk_mul_f32 v[16:17], v[16:17], v[24:25]
	v_pk_mul_f32 v[14:15], v[14:15], v[22:23]
	global_store_dwordx4 v[20:21], v[14:17], off
	s_andn2_b64 vcc, exec, s[0:1]
	s_mov_b64 s[0:1], -1
	v_pk_mul_f32 v[14:15], v[42:43], v[18:19] op_sel_hi:[1,0]
	v_pk_mul_f32 v[16:17], v[44:45], v[18:19] op_sel_hi:[1,0]
	v_pk_mul_f32 v[10:11], v[10:11], v[14:15]
	v_pk_mul_f32 v[12:13], v[12:13], v[16:17]
	global_store_dwordx4 v[20:21], v[10:13], off offset:16
	s_nop 1
	v_pk_mul_f32 v[10:11], v[38:39], v[18:19] op_sel_hi:[1,0]
	v_pk_mul_f32 v[12:13], v[40:41], v[18:19] op_sel_hi:[1,0]
	v_pk_mul_f32 v[6:7], v[6:7], v[10:11]
	v_pk_mul_f32 v[8:9], v[8:9], v[12:13]
	global_store_dwordx4 v[20:21], v[6:9], off offset:512
	s_nop 1
	v_pk_mul_f32 v[6:7], v[34:35], v[18:19] op_sel_hi:[1,0]
	v_pk_mul_f32 v[8:9], v[36:37], v[18:19] op_sel_hi:[1,0]
	v_pk_mul_f32 v[2:3], v[2:3], v[6:7]
	v_pk_mul_f32 v[4:5], v[4:5], v[8:9]
	global_store_dwordx4 v[20:21], v[2:5], off offset:528
	s_cbranch_vccnz .LBB0_1136
	s_andn2_b64 vcc, exec, s[4:5]
	s_cbranch_vccnz .LBB0_1135
	s_barrier
	s_branch .LBB0_1135
